# oproj epilogue: 16 gate loads hoisted ahead of the ACC-to-LDS staging and barrier, consumer loop regularised with double-buffered ds_read
# baseline (speedup 1.0000x reference)
.LBB0_150:
	s_mov_b32 s12, 0
	s_waitcnt vmcnt(0)
	s_lshl_b32 s16, s41, 1
	s_add_u32 s16, s6, s16
	s_addc_u32 s17, s7, 0
	s_lshl_b64 vcc, s[10:11], 1
	s_add_u32 s16, s16, vcc_lo
	s_addc_u32 s17, s17, vcc_hi
	v_lshl_add_u64 v[202:203], s[16:17], 0, v[0:1]
	s_mov_b64 s[16:17], 0x2000
	v_lshl_add_u64 v[202:203], v[202:203], 0, s[16:17]
	v_add_u32_e32 v204, s25, v69
	v_mad_i64_i32 v[204:205], vcc, v204, s96, v[202:203]
	global_load_dwordx2 v[218:219], v[204:205], off
	v_add_u32_e32 v204, s25, v156
	v_mad_i64_i32 v[204:205], vcc, v204, s96, v[202:203]
	global_load_dwordx2 v[220:221], v[204:205], off
	v_add_u32_e32 v204, s25, v157
	v_mad_i64_i32 v[204:205], vcc, v204, s96, v[202:203]
	global_load_dwordx2 v[222:223], v[204:205], off
	v_add_u32_e32 v204, s25, v158
	v_mad_i64_i32 v[204:205], vcc, v204, s96, v[202:203]
	global_load_dwordx2 v[224:225], v[204:205], off
	v_add_u32_e32 v204, s25, v159
	v_mad_i64_i32 v[204:205], vcc, v204, s96, v[202:203]
	global_load_dwordx2 v[226:227], v[204:205], off
	v_add_u32_e32 v204, s25, v160
	v_mad_i64_i32 v[204:205], vcc, v204, s96, v[202:203]
	global_load_dwordx2 v[228:229], v[204:205], off
	v_add_u32_e32 v204, s25, v161
	v_mad_i64_i32 v[204:205], vcc, v204, s96, v[202:203]
	global_load_dwordx2 v[230:231], v[204:205], off
	v_add_u32_e32 v204, s25, v162
	v_mad_i64_i32 v[204:205], vcc, v204, s96, v[202:203]
	global_load_dwordx2 v[232:233], v[204:205], off
	v_add_u32_e32 v204, s25, v163
	v_mad_i64_i32 v[204:205], vcc, v204, s96, v[202:203]
	global_load_dwordx2 v[234:235], v[204:205], off
	v_add_u32_e32 v204, s25, v164
	v_mad_i64_i32 v[204:205], vcc, v204, s96, v[202:203]
	global_load_dwordx2 v[236:237], v[204:205], off
	v_add_u32_e32 v204, s25, v165
	v_mad_i64_i32 v[204:205], vcc, v204, s96, v[202:203]
	global_load_dwordx2 v[238:239], v[204:205], off
	v_add_u32_e32 v204, s25, v166
	v_mad_i64_i32 v[204:205], vcc, v204, s96, v[202:203]
	global_load_dwordx2 v[240:241], v[204:205], off
	v_add_u32_e32 v204, s25, v167
	v_mad_i64_i32 v[204:205], vcc, v204, s96, v[202:203]
	global_load_dwordx2 v[242:243], v[204:205], off
	v_add_u32_e32 v204, s25, v168
	v_mad_i64_i32 v[204:205], vcc, v204, s96, v[202:203]
	global_load_dwordx2 v[244:245], v[204:205], off
	v_add_u32_e32 v204, s25, v169
	v_mad_i64_i32 v[204:205], vcc, v204, s96, v[202:203]
	global_load_dwordx2 v[246:247], v[204:205], off
	v_add_u32_e32 v204, s25, v175
	v_mad_i64_i32 v[204:205], vcc, v204, s96, v[202:203]
	global_load_dwordx2 v[248:249], v[204:205], off
	ds_write2_b32 v155, v6, v50 offset1:16
	v_add_u32_e32 v6, 0x400, v155
	ds_write2_b32 v6, v7, v51 offset0:4 offset1:20
	v_add_u32_e32 v7, 0x800, v155
	ds_write2_b32 v7, v8, v52 offset0:8 offset1:24
	v_add_u32_e32 v8, 0xc00, v155
	ds_write2_b32 v8, v9, v53 offset0:12 offset1:28
	v_add_u32_e32 v9, 0x4000, v155
	ds_write2_b32 v9, v42, v34 offset0:64 offset1:80
	v_add_u32_e32 v34, 0x4400, v155
	ds_write2_b32 v34, v43, v35 offset0:68 offset1:84
	v_add_u32_e32 v35, 0x4800, v155
	ds_write2_b32 v35, v44, v36 offset0:72 offset1:88
	v_add_u32_e32 v36, 0x4c00, v155
	ds_write2_b32 v36, v45, v37 offset0:76 offset1:92
	v_add_u32_e32 v37, 0x8000, v155
	ds_write2_b32 v37, v30, v26 offset0:128 offset1:144
	v_add_u32_e32 v26, 0x8400, v155
	s_ashr_i32 s13, s12, 31
	ds_write2_b32 v26, v31, v27 offset0:132 offset1:148
	v_add_u32_e32 v27, 0x8800, v155
	s_lshl_b64 s[14:15], s[12:13], 1
	ds_write2_b32 v27, v32, v28 offset0:136 offset1:152
	v_add_u32_e32 v28, 0x8c00, v155
	s_add_u32 s0, s6, s14
	ds_write2_b32 v28, v33, v29 offset0:140 offset1:156
	v_add_u32_e32 v29, 0xc000, v155
	s_addc_u32 s13, s7, s15
	s_lshl_b32 s14, s41, 1
	ds_write2_b32 v29, v22, v10 offset0:192 offset1:208
	v_add_u32_e32 v10, 0xc400, v155
	s_add_u32 s14, s0, s14
	ds_write2_b32 v10, v23, v11 offset0:196 offset1:212
	v_add_u32_e32 v11, 0xc800, v155
	s_addc_u32 s15, s13, 0
	ds_write2_b32 v11, v24, v12 offset0:200 offset1:216
	v_add_u32_e32 v12, 0xcc00, v155
	s_add_i32 s0, s12, s25
	s_lshl_b64 s[12:13], s[10:11], 1
	ds_write2_b32 v12, v25, v13 offset0:204 offset1:220
	ds_write2_b32 v155, v18, v62 offset0:128 offset1:144
	ds_write2_b32 v6, v19, v63 offset0:132 offset1:148
	ds_write2_b32 v7, v20, v64 offset0:136 offset1:152
	ds_write2_b32 v8, v21, v65 offset0:140 offset1:156
	ds_write2_b32 v9, v58, v54 offset0:192 offset1:208
	ds_write2_b32 v34, v59, v55 offset0:196 offset1:212
	ds_write2_b32 v35, v60, v56 offset0:200 offset1:216
	ds_write2_b32 v36, v61, v57 offset0:204 offset1:220
	ds_write2_b32 v26, v46, v38 offset1:16
	ds_write2_b32 v27, v47, v39 offset0:4 offset1:20
	ds_write2_b32 v28, v48, v40 offset0:8 offset1:24
	v_add_u32_e32 v6, 0x9000, v155
	s_add_u32 s14, s14, s12
	ds_write2_b32 v6, v49, v41 offset0:12 offset1:28
	ds_write2_b32 v10, v14, v2 offset0:64 offset1:80
	ds_write2_b32 v11, v15, v3 offset0:68 offset1:84
	ds_write2_b32 v12, v16, v4 offset0:72 offset1:88
	v_add_u32_e32 v2, 0xd000, v155
	s_addc_u32 s15, s15, s13
	ds_write2_b32 v2, v17, v5 offset0:76 offset1:92
	s_waitcnt lgkmcnt(0)
	s_barrier
	s_add_i32 s40, s40, 1
	s_cmp_eq_u32 s40, 3
	ds_read_b128 v[4:7], v176
	ds_read_b128 v[8:11], v177
	s_waitcnt vmcnt(15)
	v_lshlrev_b32_e32 v12, 16, v218
	v_and_b32_e32 v13, 0xffff0000, v218
	v_lshlrev_b32_e32 v14, 16, v219
	v_and_b32_e32 v15, 0xffff0000, v219
	s_waitcnt lgkmcnt(1)
	v_pk_fma_f32 v[140:141], v[4:5], v[12:13], v[140:141]
	v_pk_fma_f32 v[138:139], v[6:7], v[14:15], v[138:139]
	ds_read_b128 v[4:7], v178
	s_waitcnt vmcnt(14)
	v_lshlrev_b32_e32 v12, 16, v220
	v_and_b32_e32 v13, 0xffff0000, v220
	v_lshlrev_b32_e32 v14, 16, v221
	v_and_b32_e32 v15, 0xffff0000, v221
	s_waitcnt lgkmcnt(1)
	v_pk_fma_f32 v[136:137], v[8:9], v[12:13], v[136:137]
	v_pk_fma_f32 v[134:135], v[10:11], v[14:15], v[134:135]
	ds_read_b128 v[8:11], v179
	s_waitcnt vmcnt(13)
	v_lshlrev_b32_e32 v12, 16, v222
	v_and_b32_e32 v13, 0xffff0000, v222
	v_lshlrev_b32_e32 v14, 16, v223
	v_and_b32_e32 v15, 0xffff0000, v223
	s_waitcnt lgkmcnt(1)
	v_pk_fma_f32 v[132:133], v[4:5], v[12:13], v[132:133]
	v_pk_fma_f32 v[130:131], v[6:7], v[14:15], v[130:131]
	ds_read_b128 v[4:7], v180
	s_waitcnt vmcnt(12)
	v_lshlrev_b32_e32 v12, 16, v224
	v_and_b32_e32 v13, 0xffff0000, v224
	v_lshlrev_b32_e32 v14, 16, v225
	v_and_b32_e32 v15, 0xffff0000, v225
	s_waitcnt lgkmcnt(1)
	v_pk_fma_f32 v[128:129], v[8:9], v[12:13], v[128:129]
	v_pk_fma_f32 v[126:127], v[10:11], v[14:15], v[126:127]
	ds_read_b128 v[8:11], v181
	s_waitcnt vmcnt(11)
	v_lshlrev_b32_e32 v12, 16, v226
	v_and_b32_e32 v13, 0xffff0000, v226
	v_lshlrev_b32_e32 v14, 16, v227
	v_and_b32_e32 v15, 0xffff0000, v227
	s_waitcnt lgkmcnt(1)
	v_pk_fma_f32 v[124:125], v[4:5], v[12:13], v[124:125]
	v_pk_fma_f32 v[122:123], v[6:7], v[14:15], v[122:123]
	ds_read_b128 v[4:7], v182
	s_waitcnt vmcnt(10)
	v_lshlrev_b32_e32 v12, 16, v228
	v_and_b32_e32 v13, 0xffff0000, v228
	v_lshlrev_b32_e32 v14, 16, v229
	v_and_b32_e32 v15, 0xffff0000, v229
	s_waitcnt lgkmcnt(1)
	v_pk_fma_f32 v[120:121], v[8:9], v[12:13], v[120:121]
	v_pk_fma_f32 v[118:119], v[10:11], v[14:15], v[118:119]
	ds_read_b128 v[8:11], v183
	s_waitcnt vmcnt(9)
	v_lshlrev_b32_e32 v12, 16, v230
	v_and_b32_e32 v13, 0xffff0000, v230
	v_lshlrev_b32_e32 v14, 16, v231
	v_and_b32_e32 v15, 0xffff0000, v231
	s_waitcnt lgkmcnt(1)
	v_pk_fma_f32 v[116:117], v[4:5], v[12:13], v[116:117]
	v_pk_fma_f32 v[114:115], v[6:7], v[14:15], v[114:115]
	ds_read_b128 v[4:7], v184
	s_waitcnt vmcnt(8)
	v_lshlrev_b32_e32 v12, 16, v232
	v_and_b32_e32 v13, 0xffff0000, v232
	v_lshlrev_b32_e32 v14, 16, v233
	v_and_b32_e32 v15, 0xffff0000, v233
	s_waitcnt lgkmcnt(1)
	v_pk_fma_f32 v[112:113], v[8:9], v[12:13], v[112:113]
	v_pk_fma_f32 v[110:111], v[10:11], v[14:15], v[110:111]
	ds_read_b128 v[8:11], v185
	s_waitcnt vmcnt(7)
	v_lshlrev_b32_e32 v12, 16, v234
	v_and_b32_e32 v13, 0xffff0000, v234
	v_lshlrev_b32_e32 v14, 16, v235
	v_and_b32_e32 v15, 0xffff0000, v235
	s_waitcnt lgkmcnt(1)
	v_pk_fma_f32 v[108:109], v[4:5], v[12:13], v[108:109]
	v_pk_fma_f32 v[106:107], v[6:7], v[14:15], v[106:107]
	ds_read_b128 v[4:7], v186
	s_waitcnt vmcnt(6)
	v_lshlrev_b32_e32 v12, 16, v236
	v_and_b32_e32 v13, 0xffff0000, v236
	v_lshlrev_b32_e32 v14, 16, v237
	v_and_b32_e32 v15, 0xffff0000, v237
	s_waitcnt lgkmcnt(1)
	v_pk_fma_f32 v[104:105], v[8:9], v[12:13], v[104:105]
	v_pk_fma_f32 v[102:103], v[10:11], v[14:15], v[102:103]
	ds_read_b128 v[8:11], v187
	s_waitcnt vmcnt(5)
	v_lshlrev_b32_e32 v12, 16, v238
	v_and_b32_e32 v13, 0xffff0000, v238
	v_lshlrev_b32_e32 v14, 16, v239
	v_and_b32_e32 v15, 0xffff0000, v239
	s_waitcnt lgkmcnt(1)
	v_pk_fma_f32 v[100:101], v[4:5], v[12:13], v[100:101]
	v_pk_fma_f32 v[98:99], v[6:7], v[14:15], v[98:99]
	ds_read_b128 v[4:7], v188
	s_waitcnt vmcnt(4)
	v_lshlrev_b32_e32 v12, 16, v240
	v_and_b32_e32 v13, 0xffff0000, v240
	v_lshlrev_b32_e32 v14, 16, v241
	v_and_b32_e32 v15, 0xffff0000, v241
	s_waitcnt lgkmcnt(1)
	v_pk_fma_f32 v[96:97], v[8:9], v[12:13], v[96:97]
	v_pk_fma_f32 v[94:95], v[10:11], v[14:15], v[94:95]
	ds_read_b128 v[8:11], v189
	s_waitcnt vmcnt(3)
	v_lshlrev_b32_e32 v12, 16, v242
	v_and_b32_e32 v13, 0xffff0000, v242
	v_lshlrev_b32_e32 v14, 16, v243
	v_and_b32_e32 v15, 0xffff0000, v243
	s_waitcnt lgkmcnt(1)
	v_pk_fma_f32 v[92:93], v[4:5], v[12:13], v[92:93]
	v_pk_fma_f32 v[90:91], v[6:7], v[14:15], v[90:91]
	ds_read_b128 v[4:7], v190
	s_waitcnt vmcnt(2)
	v_lshlrev_b32_e32 v12, 16, v244
	v_and_b32_e32 v13, 0xffff0000, v244
	v_lshlrev_b32_e32 v14, 16, v245
	v_and_b32_e32 v15, 0xffff0000, v245
	s_waitcnt lgkmcnt(1)
	v_pk_fma_f32 v[88:89], v[8:9], v[12:13], v[88:89]
	v_pk_fma_f32 v[86:87], v[10:11], v[14:15], v[86:87]
	ds_read_b128 v[8:11], v191
	s_waitcnt vmcnt(1)
	v_lshlrev_b32_e32 v12, 16, v246
	v_and_b32_e32 v13, 0xffff0000, v246
	v_lshlrev_b32_e32 v14, 16, v247
	v_and_b32_e32 v15, 0xffff0000, v247
	s_waitcnt lgkmcnt(1)
	v_pk_fma_f32 v[84:85], v[4:5], v[12:13], v[84:85]
	v_pk_fma_f32 v[82:83], v[6:7], v[14:15], v[82:83]
	s_waitcnt vmcnt(0)
	v_lshlrev_b32_e32 v12, 16, v248
	v_and_b32_e32 v13, 0xffff0000, v248
	v_lshlrev_b32_e32 v14, 16, v249
	v_and_b32_e32 v15, 0xffff0000, v249
	s_waitcnt lgkmcnt(0)
	s_mov_b64 s[14:15], 0x100000
	v_pk_fma_f32 v[80:81], v[8:9], v[12:13], v[80:81]
	v_pk_fma_f32 v[78:79], v[10:11], v[14:15], v[78:79]
	v_lshl_add_u64 v[144:145], v[144:145], 0, s[14:15]
	s_barrier
	s_cbranch_scc1 .LBB0_148
